# epilogue de-serialisation in EpiRes (out/down GEMM): second batch of residual loads issued early (6 at the epilogue top into epilogue-dead registers, 2 into first-batch quads once consumed) instead of
# baseline (speedup 1.0000x reference)
.LBB0_455:
	s_lshl_b32 s4, s69, 8
	v_mov_b32_e32 v132, v182
	v_mov_b32_e32 v130, v183
	s_add_i32 s4, s4, s49
	s_nop 0
	v_add_u32_e32 v172, s4, v130
	v_lshrrev_b32_e32 v194, 2, v213
	v_and_b32_e32 v195, 3, v213
	v_lshlrev_b32_e32 v196, 6, v195
	v_lshl_add_u32 v196, v194, 2, v196
	v_and_b32_e32 v197, 15, v213
	v_lshlrev_b32_e32 v197, 4, v197
	v_lshrrev_b32_e32 v198, 4, v213
	v_lshl_add_u32 v197, v198, 2, v197
	v_add_u32_e32 v198, s4, v194
	v_ashrrev_i32_e32 v199, 31, v198
	s_lshl_b32 s4, s68, 8
	s_or_b32 s4, s4, s50
	v_lshl_add_u32 v130, v195, 3, s4
	v_ashrrev_i32_e32 v131, 31, v130
	v_ashrrev_i32_e32 v173, 31, v172
	v_lshlrev_b64 v[168:169], 1, v[130:131]
	v_lshl_add_u64 v[170:171], s[12:13], 0, v[168:169]
	v_lshlrev_b64 v[180:181], 11, v[198:199]
	v_lshl_add_u64 v[130:131], v[170:171], 0, v[180:181]
	global_load_dwordx4 v[188:191], v[130:131], off
	global_load_dwordx4 v[154:157], v[130:131], off offset:256
	s_lshl_b32 s4, s68, 2
	s_or_b32 s4, s4, s47
	s_ashr_i32 s5, s4, 31
	s_lshl_b64 s[30:31], s[4:5], 17
	s_mov_b64 s[4:5], 0x8000
	v_lshl_add_u64 v[178:179], v[180:181], 0, s[4:5]
	v_lshl_add_u64 v[130:131], v[170:171], 0, v[178:179]
	global_load_dwordx4 v[150:153], v[130:131], off
	global_load_dwordx4 v[146:149], v[130:131], off offset:256
	s_mov_b64 s[4:5], 0x10000
	v_lshl_add_u64 v[176:177], v[180:181], 0, s[4:5]
	v_lshl_add_u64 v[130:131], v[170:171], 0, v[176:177]
	global_load_dwordx4 v[142:145], v[130:131], off
	global_load_dwordx4 v[138:141], v[130:131], off offset:256
	s_mov_b64 s[4:5], 0x18000
	v_lshl_add_u64 v[174:175], v[180:181], 0, s[4:5]
	v_lshl_add_u64 v[130:131], v[170:171], 0, v[174:175]
	v_cmp_eq_u32_e32 vcc, 0, v132
	global_load_dwordx4 v[134:137], v[130:131], off
	s_nop 0
	global_load_dwordx4 v[130:133], v[130:131], off offset:256
	s_mov_b64 s[4:5], 0x40000
	v_lshl_add_u64 v[234:235], v[180:181], 0, s[4:5]
	v_lshl_add_u64 v[234:235], v[170:171], 0, v[234:235]
	global_load_dwordx4 v[204:207], v[234:235], off
	global_load_dwordx4 v[222:225], v[234:235], off offset:256
	s_mov_b64 s[4:5], 0x48000
	v_lshl_add_u64 v[234:235], v[180:181], 0, s[4:5]
	v_lshl_add_u64 v[234:235], v[170:171], 0, v[234:235]
	global_load_dwordx4 v[226:229], v[234:235], off
	global_load_dwordx4 v[230:233], v[234:235], off offset:256
	s_mov_b64 s[4:5], 0x50000
	v_lshl_add_u64 v[234:235], v[180:181], 0, s[4:5]
	v_lshl_add_u64 v[234:235], v[170:171], 0, v[234:235]
	global_load_dwordx4 v[238:241], v[234:235], off
	global_load_dwordx4 v[250:253], v[234:235], off offset:256
	s_mov_b64 s[4:5], 0x58000
	v_lshl_add_u64 v[234:235], v[180:181], 0, s[4:5]
	v_lshl_add_u64 v[242:243], v[170:171], 0, v[234:235]
	v_lshl_add_u64 v[180:181], s[12:13], 0, v[180:181]
	v_lshl_add_u64 v[180:181], v[180:181], 0, v[168:169]
	s_add_u32 s4, s14, s30
	s_addc_u32 s5, s15, s31
	s_waitcnt vmcnt(6)
	ds_bpermute_b32 v188, v197, v188
	ds_bpermute_b32 v189, v197, v189
	ds_bpermute_b32 v190, v197, v190
	ds_bpermute_b32 v191, v197, v191
	ds_bpermute_b32 v154, v197, v154
	ds_bpermute_b32 v155, v197, v155
	ds_bpermute_b32 v156, v197, v156
	ds_bpermute_b32 v157, v197, v157
	ds_bpermute_b32 v150, v197, v150
	ds_bpermute_b32 v151, v197, v151
	ds_bpermute_b32 v152, v197, v152
	ds_bpermute_b32 v153, v197, v153
	ds_bpermute_b32 v146, v197, v146
	ds_bpermute_b32 v147, v197, v147
	ds_bpermute_b32 v148, v197, v148
	ds_bpermute_b32 v149, v197, v149
	ds_bpermute_b32 v142, v197, v142
	ds_bpermute_b32 v143, v197, v143
	ds_bpermute_b32 v144, v197, v144
	ds_bpermute_b32 v145, v197, v145
	ds_bpermute_b32 v138, v197, v138
	ds_bpermute_b32 v139, v197, v139
	ds_bpermute_b32 v140, v197, v140
	ds_bpermute_b32 v141, v197, v141
	ds_bpermute_b32 v134, v197, v134
	ds_bpermute_b32 v135, v197, v135
	ds_bpermute_b32 v136, v197, v136
	ds_bpermute_b32 v137, v197, v137
	ds_bpermute_b32 v130, v197, v130
	ds_bpermute_b32 v131, v197, v131
	ds_bpermute_b32 v132, v197, v132
	ds_bpermute_b32 v133, v197, v133
	s_waitcnt lgkmcnt(0)
	v_lshlrev_b32_e32 v192, 16, v188
	v_and_b32_e32 v193, 0xffff0000, v188
	v_lshlrev_b32_e32 v188, 16, v189
	v_and_b32_e32 v189, 0xffff0000, v189
	v_pk_add_f32 v[126:127], v[126:127], v[192:193]
	v_pk_add_f32 v[128:129], v[128:129], v[188:189]
	v_cvt_pk_bf16_f32 v126, v126, v127
	v_cvt_pk_bf16_f32 v127, v128, v129
	v_lshlrev_b32_e32 v128, 16, v190
	v_and_b32_e32 v129, 0xffff0000, v190
	v_pk_add_f32 v[122:123], v[122:123], v[128:129]
	s_nop 0
	v_cvt_pk_bf16_f32 v128, v122, v123
	v_lshlrev_b32_e32 v122, 16, v191
	v_and_b32_e32 v123, 0xffff0000, v191
	global_load_dwordx4 v[188:191], v[242:243], off
	v_pk_add_f32 v[122:123], v[124:125], v[122:123]
	v_and_b32_e32 v124, 0xffff0000, v127
	v_cvt_pk_bf16_f32 v129, v122, v123
	v_and_b32_e32 v123, 0xffff0000, v126
	v_lshlrev_b32_e32 v122, 16, v126
	v_mul_f32_e32 v123, v123, v123
	v_fmac_f32_e32 v123, v122, v122
	v_lshlrev_b32_e32 v122, 16, v127
	v_mul_f32_e32 v124, v124, v124
	v_fmac_f32_e32 v124, v122, v122
	v_add_f32_e32 v122, v123, v124
	v_and_b32_e32 v124, 0xffff0000, v128
	v_lshlrev_b32_e32 v123, 16, v128
	v_mul_f32_e32 v124, v124, v124
	v_fmac_f32_e32 v124, v123, v123
	v_add_f32_e32 v122, v124, v122
	v_and_b32_e32 v124, 0xffff0000, v129
	v_lshlrev_b32_e32 v123, 16, v129
	v_mul_f32_e32 v124, v124, v124
	v_fmac_f32_e32 v124, v123, v123
	v_add_f32_e32 v124, v124, v122
	v_lshlrev_b32_e32 v122, 16, v154
	v_and_b32_e32 v123, 0xffff0000, v154
	v_pk_add_f32 v[118:119], v[118:119], v[122:123]
	v_lshlrev_b32_e32 v122, 16, v155
	v_and_b32_e32 v123, 0xffff0000, v155
	v_pk_add_f32 v[120:121], v[120:121], v[122:123]
	v_cvt_pk_bf16_f32 v118, v118, v119
	v_cvt_pk_bf16_f32 v119, v120, v121
	v_lshlrev_b32_e32 v120, 16, v156
	v_and_b32_e32 v121, 0xffff0000, v156
	v_pk_add_f32 v[114:115], v[114:115], v[120:121]
	ds_bpermute_b32 v200, v196, v126
	ds_bpermute_b32 v201, v196, v127
	ds_bpermute_b32 v202, v196, v128
	ds_bpermute_b32 v203, v196, v129
	s_waitcnt lgkmcnt(0)
	global_store_dwordx4 v[180:181], v[200:203], off
	v_cvt_pk_bf16_f32 v120, v114, v115
	v_lshlrev_b32_e32 v114, 16, v157
	v_and_b32_e32 v115, 0xffff0000, v157
	global_load_dwordx4 v[154:157], v[242:243], off offset:256
	v_pk_add_f32 v[114:115], v[116:117], v[114:115]
	v_and_b32_e32 v116, 0xffff0000, v119
	v_cvt_pk_bf16_f32 v121, v114, v115
	v_and_b32_e32 v115, 0xffff0000, v118
	v_lshlrev_b32_e32 v114, 16, v118
	v_mul_f32_e32 v115, v115, v115
	v_fmac_f32_e32 v115, v114, v114
	v_lshlrev_b32_e32 v114, 16, v119
	v_mul_f32_e32 v116, v116, v116
	v_fmac_f32_e32 v116, v114, v114
	v_add_f32_e32 v114, v115, v116
	v_and_b32_e32 v116, 0xffff0000, v120
	v_lshlrev_b32_e32 v115, 16, v120
	v_mul_f32_e32 v116, v116, v116
	v_fmac_f32_e32 v116, v115, v115
	v_add_f32_e32 v114, v116, v114
	v_and_b32_e32 v116, 0xffff0000, v121
	v_lshlrev_b32_e32 v115, 16, v121
	v_mul_f32_e32 v116, v116, v116
	v_fmac_f32_e32 v116, v115, v115
	v_add_f32_e32 v114, v116, v114
	v_lshlrev_b32_e32 v116, 16, v150
	v_and_b32_e32 v117, 0xffff0000, v150
	v_pk_add_f32 v[110:111], v[110:111], v[116:117]
	v_lshlrev_b32_e32 v116, 16, v151
	v_and_b32_e32 v117, 0xffff0000, v151
	v_pk_add_f32 v[112:113], v[112:113], v[116:117]
	v_cvt_pk_bf16_f32 v110, v110, v111
	v_cvt_pk_bf16_f32 v111, v112, v113
	v_lshlrev_b32_e32 v112, 16, v152
	v_and_b32_e32 v113, 0xffff0000, v152
	v_pk_add_f32 v[106:107], v[106:107], v[112:113]
	ds_bpermute_b32 v200, v196, v118
	ds_bpermute_b32 v201, v196, v119
	ds_bpermute_b32 v202, v196, v120
	ds_bpermute_b32 v203, v196, v121
	s_waitcnt lgkmcnt(0)
	global_store_dwordx4 v[180:181], v[200:203], off offset:256
	v_cvt_pk_bf16_f32 v112, v106, v107
	v_lshlrev_b32_e32 v106, 16, v153
	v_and_b32_e32 v107, 0xffff0000, v153
	v_pk_add_f32 v[106:107], v[108:109], v[106:107]
	v_add_f32_e32 v118, v124, v114
	v_cvt_pk_bf16_f32 v113, v106, v107
	v_lshlrev_b32_e32 v106, 16, v146
	v_and_b32_e32 v107, 0xffff0000, v146
	v_pk_add_f32 v[102:103], v[102:103], v[106:107]
	v_lshlrev_b32_e32 v106, 16, v147
	v_and_b32_e32 v107, 0xffff0000, v147
	v_pk_add_f32 v[104:105], v[104:105], v[106:107]
	v_cvt_pk_bf16_f32 v102, v102, v103
	v_cvt_pk_bf16_f32 v103, v104, v105
	v_lshlrev_b32_e32 v104, 16, v148
	v_and_b32_e32 v105, 0xffff0000, v148
	v_pk_add_f32 v[94:95], v[94:95], v[104:105]
	v_lshl_add_u64 v[114:115], s[12:13], 0, v[178:179]
	v_cvt_pk_bf16_f32 v104, v94, v95
	v_lshlrev_b32_e32 v94, 16, v149
	v_and_b32_e32 v95, 0xffff0000, v149
	v_pk_add_f32 v[94:95], v[96:97], v[94:95]
	v_lshlrev_b32_e32 v96, 16, v143
	v_cvt_pk_bf16_f32 v105, v94, v95
	v_lshl_add_u64 v[94:95], s[12:13], 0, v[176:177]
	v_lshl_add_u64 v[106:107], v[94:95], 0, v[168:169]
	v_lshlrev_b32_e32 v94, 16, v142
	v_and_b32_e32 v95, 0xffff0000, v142
	v_and_b32_e32 v97, 0xffff0000, v143
	v_pk_add_f32 v[94:95], v[98:99], v[94:95]
	v_pk_add_f32 v[96:97], v[100:101], v[96:97]
	v_cvt_pk_bf16_f32 v94, v94, v95
	v_cvt_pk_bf16_f32 v95, v96, v97
	v_lshlrev_b32_e32 v96, 16, v144
	v_and_b32_e32 v97, 0xffff0000, v144
	v_pk_add_f32 v[90:91], v[90:91], v[96:97]
	v_lshl_add_u64 v[114:115], v[114:115], 0, v[168:169]
	v_cvt_pk_bf16_f32 v96, v90, v91
	v_lshlrev_b32_e32 v90, 16, v145
	v_and_b32_e32 v91, 0xffff0000, v145
	v_pk_add_f32 v[90:91], v[92:93], v[90:91]
	v_lshl_add_u64 v[98:99], v[172:173], 2, s[4:5]
	v_cvt_pk_bf16_f32 v97, v90, v91
	v_lshlrev_b32_e32 v90, 16, v138
	v_and_b32_e32 v91, 0xffff0000, v138
	v_pk_add_f32 v[86:87], v[86:87], v[90:91]
	v_lshlrev_b32_e32 v90, 16, v139
	v_and_b32_e32 v91, 0xffff0000, v139
	v_pk_add_f32 v[88:89], v[88:89], v[90:91]
	v_cvt_pk_bf16_f32 v86, v86, v87
	v_cvt_pk_bf16_f32 v87, v88, v89
	v_lshlrev_b32_e32 v88, 16, v140
	v_and_b32_e32 v89, 0xffff0000, v140
	v_pk_add_f32 v[78:79], v[78:79], v[88:89]
	ds_bpermute_b32 v200, v196, v110
	ds_bpermute_b32 v201, v196, v111
	ds_bpermute_b32 v202, v196, v112
	ds_bpermute_b32 v203, v196, v113
	s_waitcnt lgkmcnt(0)
	global_store_dwordx4 v[114:115], v[200:203], off
	v_cvt_pk_bf16_f32 v88, v78, v79
	v_lshlrev_b32_e32 v78, 16, v141
	v_and_b32_e32 v79, 0xffff0000, v141
	v_pk_add_f32 v[78:79], v[80:81], v[78:79]
	v_lshlrev_b32_e32 v80, 16, v135
	v_cvt_pk_bf16_f32 v89, v78, v79
	v_lshl_add_u64 v[78:79], s[12:13], 0, v[174:175]
	v_lshl_add_u64 v[90:91], v[78:79], 0, v[168:169]
	v_lshlrev_b32_e32 v78, 16, v134
	v_and_b32_e32 v79, 0xffff0000, v134
	v_and_b32_e32 v81, 0xffff0000, v135
	v_pk_add_f32 v[78:79], v[82:83], v[78:79]
	v_pk_add_f32 v[80:81], v[84:85], v[80:81]
	v_cvt_pk_bf16_f32 v78, v78, v79
	v_cvt_pk_bf16_f32 v79, v80, v81
	v_lshlrev_b32_e32 v80, 16, v136
	v_and_b32_e32 v81, 0xffff0000, v136
	v_pk_add_f32 v[74:75], v[74:75], v[80:81]
	ds_bpermute_b32 v200, v196, v102
	ds_bpermute_b32 v201, v196, v103
	ds_bpermute_b32 v202, v196, v104
	ds_bpermute_b32 v203, v196, v105
	s_waitcnt lgkmcnt(0)
	global_store_dwordx4 v[114:115], v[200:203], off offset:256
	v_cvt_pk_bf16_f32 v80, v74, v75
	v_lshlrev_b32_e32 v74, 16, v137
	v_and_b32_e32 v75, 0xffff0000, v137
	v_pk_add_f32 v[74:75], v[76:77], v[74:75]
	ds_bpermute_b32 v200, v196, v94
	ds_bpermute_b32 v201, v196, v95
	ds_bpermute_b32 v202, v196, v96
	ds_bpermute_b32 v203, v196, v97
	s_waitcnt lgkmcnt(0)
	global_store_dwordx4 v[106:107], v[200:203], off
	v_cvt_pk_bf16_f32 v81, v74, v75
	v_lshlrev_b32_e32 v74, 16, v130
	v_and_b32_e32 v75, 0xffff0000, v130
	v_pk_add_f32 v[70:71], v[70:71], v[74:75]
	v_lshlrev_b32_e32 v74, 16, v131
	v_and_b32_e32 v75, 0xffff0000, v131
	v_pk_add_f32 v[72:73], v[72:73], v[74:75]
	v_cvt_pk_bf16_f32 v70, v70, v71
	v_cvt_pk_bf16_f32 v71, v72, v73
	v_lshlrev_b32_e32 v72, 16, v132
	v_and_b32_e32 v73, 0xffff0000, v132
	v_pk_add_f32 v[66:67], v[66:67], v[72:73]
	ds_bpermute_b32 v200, v196, v86
	ds_bpermute_b32 v201, v196, v87
	ds_bpermute_b32 v202, v196, v88
	ds_bpermute_b32 v203, v196, v89
	s_waitcnt lgkmcnt(0)
	global_store_dwordx4 v[106:107], v[200:203], off offset:256
	v_cvt_pk_bf16_f32 v72, v66, v67
	v_lshlrev_b32_e32 v66, 16, v133
	v_and_b32_e32 v67, 0xffff0000, v133
	v_pk_add_f32 v[66:67], v[68:69], v[66:67]
	ds_bpermute_b32 v200, v196, v78
	ds_bpermute_b32 v201, v196, v79
	ds_bpermute_b32 v202, v196, v80
	ds_bpermute_b32 v203, v196, v81
	s_waitcnt lgkmcnt(0)
	global_store_dwordx4 v[90:91], v[200:203], off
	v_cvt_pk_bf16_f32 v73, v66, v67
	ds_bpermute_b32 v66, v185, v118
	ds_bpermute_b32 v200, v196, v70
	ds_bpermute_b32 v201, v196, v71
	ds_bpermute_b32 v202, v196, v72
	ds_bpermute_b32 v203, v196, v73
	s_waitcnt lgkmcnt(0)
	global_store_dwordx4 v[90:91], v[200:203], off offset:256
	s_waitcnt lgkmcnt(0)
	v_add_f32_e32 v66, v118, v66
	ds_bpermute_b32 v67, v186, v66
	s_and_saveexec_b64 s[30:31], vcc
	s_cbranch_execz .LBB0_457
	s_waitcnt lgkmcnt(0)
	v_add_f32_e32 v66, v66, v67
	global_store_dword v[98:99], v66, off

.LBB0_463:
	s_or_b64 exec, exec, s[30:31]
	s_waitcnt lgkmcnt(0)
	v_lshlrev_b64 v[66:67], 11, v[198:199]
	s_mov_b64 s[4:5], 0x40000
	v_lshl_add_u64 v[102:103], v[66:67], 0, s[4:5]
	v_lshl_add_u64 v[68:69], v[170:171], 0, v[102:103]
	s_mov_b64 s[4:5], 0x48000
	v_lshl_add_u64 v[100:101], v[66:67], 0, s[4:5]
	v_lshl_add_u64 v[68:69], v[170:171], 0, v[100:101]
	s_mov_b64 s[4:5], 0x50000
	v_lshl_add_u64 v[96:97], v[66:67], 0, s[4:5]
	v_lshl_add_u64 v[68:69], v[170:171], 0, v[96:97]
	s_mov_b64 s[4:5], 0x58000
	v_lshl_add_u64 v[94:95], v[66:67], 0, s[4:5]
	v_lshl_add_u64 v[66:67], v[170:171], 0, v[94:95]
	v_lshl_add_u64 v[102:103], s[12:13], 0, v[102:103]
	v_lshl_add_u64 v[102:103], v[102:103], 0, v[168:169]
	s_waitcnt vmcnt(7)
	ds_bpermute_b32 v104, v197, v204
	ds_bpermute_b32 v105, v197, v205
	ds_bpermute_b32 v106, v197, v206
	ds_bpermute_b32 v107, v197, v207
	ds_bpermute_b32 v90, v197, v222
	ds_bpermute_b32 v91, v197, v223
	ds_bpermute_b32 v92, v197, v224
	ds_bpermute_b32 v93, v197, v225
	ds_bpermute_b32 v86, v197, v226
	ds_bpermute_b32 v87, v197, v227
	ds_bpermute_b32 v88, v197, v228
	ds_bpermute_b32 v89, v197, v229
	ds_bpermute_b32 v82, v197, v230
	ds_bpermute_b32 v83, v197, v231
	ds_bpermute_b32 v84, v197, v232
	ds_bpermute_b32 v85, v197, v233
	ds_bpermute_b32 v78, v197, v238
	ds_bpermute_b32 v79, v197, v239
	ds_bpermute_b32 v80, v197, v240
	ds_bpermute_b32 v81, v197, v241
	ds_bpermute_b32 v70, v197, v250
	ds_bpermute_b32 v71, v197, v251
	ds_bpermute_b32 v72, v197, v252
	ds_bpermute_b32 v73, v197, v253
	ds_bpermute_b32 v74, v197, v188
	ds_bpermute_b32 v75, v197, v189
	ds_bpermute_b32 v76, v197, v190
	ds_bpermute_b32 v77, v197, v191
	ds_bpermute_b32 v66, v197, v154
	ds_bpermute_b32 v67, v197, v155
	ds_bpermute_b32 v68, v197, v156
	ds_bpermute_b32 v69, v197, v157
	s_waitcnt lgkmcnt(0)
	v_lshlrev_b32_e32 v108, 16, v104
	v_and_b32_e32 v109, 0xffff0000, v104
	v_lshlrev_b32_e32 v104, 16, v105
	v_and_b32_e32 v105, 0xffff0000, v105
	v_pk_add_f32 v[62:63], v[62:63], v[108:109]
	v_pk_add_f32 v[64:65], v[64:65], v[104:105]
	v_cvt_pk_bf16_f32 v62, v62, v63
	v_cvt_pk_bf16_f32 v63, v64, v65
	v_lshlrev_b32_e32 v64, 16, v106
	v_and_b32_e32 v65, 0xffff0000, v106
	v_pk_add_f32 v[58:59], v[58:59], v[64:65]
	s_nop 0
	v_cvt_pk_bf16_f32 v64, v58, v59
	v_lshlrev_b32_e32 v58, 16, v107
	v_and_b32_e32 v59, 0xffff0000, v107
	v_pk_add_f32 v[58:59], v[60:61], v[58:59]
	v_and_b32_e32 v60, 0xffff0000, v63
	v_cvt_pk_bf16_f32 v65, v58, v59
	v_and_b32_e32 v59, 0xffff0000, v62
	v_lshlrev_b32_e32 v58, 16, v62
	v_mul_f32_e32 v59, v59, v59
	v_fmac_f32_e32 v59, v58, v58
	v_lshlrev_b32_e32 v58, 16, v63
	v_mul_f32_e32 v60, v60, v60
	v_fmac_f32_e32 v60, v58, v58
	v_add_f32_e32 v58, v59, v60
	v_and_b32_e32 v60, 0xffff0000, v64
	v_lshlrev_b32_e32 v59, 16, v64
	v_mul_f32_e32 v60, v60, v60
	v_fmac_f32_e32 v60, v59, v59
	v_add_f32_e32 v58, v60, v58
	v_and_b32_e32 v60, 0xffff0000, v65
	v_lshlrev_b32_e32 v59, 16, v65
	v_mul_f32_e32 v60, v60, v60
	v_fmac_f32_e32 v60, v59, v59
	v_add_f32_e32 v60, v60, v58
	s_waitcnt vmcnt(6)
	v_lshlrev_b32_e32 v58, 16, v90
	v_and_b32_e32 v59, 0xffff0000, v90
	v_pk_add_f32 v[54:55], v[54:55], v[58:59]
	v_lshlrev_b32_e32 v58, 16, v91
	v_and_b32_e32 v59, 0xffff0000, v91
	v_pk_add_f32 v[56:57], v[56:57], v[58:59]
	v_cvt_pk_bf16_f32 v54, v54, v55
	v_cvt_pk_bf16_f32 v55, v56, v57
	v_lshlrev_b32_e32 v56, 16, v92
	v_and_b32_e32 v57, 0xffff0000, v92
	v_pk_add_f32 v[50:51], v[50:51], v[56:57]
	ds_bpermute_b32 v200, v196, v62
	ds_bpermute_b32 v201, v196, v63
	ds_bpermute_b32 v202, v196, v64
	ds_bpermute_b32 v203, v196, v65
	s_waitcnt lgkmcnt(0)
	global_store_dwordx4 v[102:103], v[200:203], off
	v_cvt_pk_bf16_f32 v56, v50, v51
	v_lshlrev_b32_e32 v50, 16, v93
	v_and_b32_e32 v51, 0xffff0000, v93
	v_pk_add_f32 v[50:51], v[52:53], v[50:51]
	v_and_b32_e32 v52, 0xffff0000, v55
	v_cvt_pk_bf16_f32 v57, v50, v51
	v_and_b32_e32 v51, 0xffff0000, v54
	v_lshlrev_b32_e32 v50, 16, v54
	v_mul_f32_e32 v51, v51, v51
	v_fmac_f32_e32 v51, v50, v50
	v_lshlrev_b32_e32 v50, 16, v55
	v_mul_f32_e32 v52, v52, v52
	v_fmac_f32_e32 v52, v50, v50
	v_add_f32_e32 v50, v51, v52
	v_and_b32_e32 v52, 0xffff0000, v56
	v_lshlrev_b32_e32 v51, 16, v56
	v_mul_f32_e32 v52, v52, v52
	v_fmac_f32_e32 v52, v51, v51
	v_add_f32_e32 v50, v52, v50
	v_and_b32_e32 v52, 0xffff0000, v57
	v_lshlrev_b32_e32 v51, 16, v57
	v_mul_f32_e32 v52, v52, v52
	v_fmac_f32_e32 v52, v51, v51
	v_add_f32_e32 v50, v52, v50
	s_waitcnt vmcnt(6)
	v_lshlrev_b32_e32 v52, 16, v86
	v_and_b32_e32 v53, 0xffff0000, v86
	v_pk_add_f32 v[46:47], v[46:47], v[52:53]
	v_lshlrev_b32_e32 v52, 16, v87
	v_and_b32_e32 v53, 0xffff0000, v87
	v_pk_add_f32 v[48:49], v[48:49], v[52:53]
	v_cvt_pk_bf16_f32 v46, v46, v47
	v_cvt_pk_bf16_f32 v47, v48, v49
	v_lshlrev_b32_e32 v48, 16, v88
	v_and_b32_e32 v49, 0xffff0000, v88
	v_pk_add_f32 v[42:43], v[42:43], v[48:49]
	ds_bpermute_b32 v200, v196, v54
	ds_bpermute_b32 v201, v196, v55
	ds_bpermute_b32 v202, v196, v56
	ds_bpermute_b32 v203, v196, v57
	s_waitcnt lgkmcnt(0)
	global_store_dwordx4 v[102:103], v[200:203], off offset:256
	v_cvt_pk_bf16_f32 v48, v42, v43
	v_lshlrev_b32_e32 v42, 16, v89
	v_and_b32_e32 v43, 0xffff0000, v89
	v_pk_add_f32 v[42:43], v[44:45], v[42:43]
	v_add_f32_e32 v54, v60, v50
	v_cvt_pk_bf16_f32 v49, v42, v43
	s_waitcnt vmcnt(6)
	v_lshlrev_b32_e32 v42, 16, v82
	v_and_b32_e32 v43, 0xffff0000, v82
	v_pk_add_f32 v[38:39], v[38:39], v[42:43]
	v_lshlrev_b32_e32 v42, 16, v83
	v_and_b32_e32 v43, 0xffff0000, v83
	v_pk_add_f32 v[40:41], v[40:41], v[42:43]
	v_cvt_pk_bf16_f32 v38, v38, v39
	v_cvt_pk_bf16_f32 v39, v40, v41
	v_lshlrev_b32_e32 v40, 16, v84
	v_and_b32_e32 v41, 0xffff0000, v84
	v_pk_add_f32 v[30:31], v[30:31], v[40:41]
	v_lshl_add_u64 v[50:51], s[12:13], 0, v[100:101]
	v_cvt_pk_bf16_f32 v40, v30, v31
	v_lshlrev_b32_e32 v30, 16, v85
	v_and_b32_e32 v31, 0xffff0000, v85
	v_pk_add_f32 v[30:31], v[32:33], v[30:31]
	s_waitcnt vmcnt(5)
	v_lshlrev_b32_e32 v32, 16, v79
	v_cvt_pk_bf16_f32 v41, v30, v31
	v_lshl_add_u64 v[30:31], s[12:13], 0, v[96:97]
	v_lshl_add_u64 v[42:43], v[30:31], 0, v[168:169]
	v_lshlrev_b32_e32 v30, 16, v78
	v_and_b32_e32 v31, 0xffff0000, v78
	v_and_b32_e32 v33, 0xffff0000, v79
	v_pk_add_f32 v[30:31], v[34:35], v[30:31]
	v_pk_add_f32 v[32:33], v[36:37], v[32:33]
	v_cvt_pk_bf16_f32 v30, v30, v31
	v_cvt_pk_bf16_f32 v31, v32, v33
	v_lshlrev_b32_e32 v32, 16, v80
	v_and_b32_e32 v33, 0xffff0000, v80
	v_pk_add_f32 v[26:27], v[26:27], v[32:33]
	v_lshl_add_u64 v[50:51], v[50:51], 0, v[168:169]
	v_cvt_pk_bf16_f32 v32, v26, v27
	v_lshlrev_b32_e32 v26, 16, v81
	v_and_b32_e32 v27, 0xffff0000, v81
	v_pk_add_f32 v[26:27], v[28:29], v[26:27]
	ds_bpermute_b32 v200, v196, v46
	ds_bpermute_b32 v201, v196, v47
	ds_bpermute_b32 v202, v196, v48
	ds_bpermute_b32 v203, v196, v49
	s_waitcnt lgkmcnt(0)
	global_store_dwordx4 v[50:51], v[200:203], off
	v_cvt_pk_bf16_f32 v33, v26, v27
	s_waitcnt vmcnt(5)
	v_lshlrev_b32_e32 v26, 16, v70
	v_and_b32_e32 v27, 0xffff0000, v70
	v_pk_add_f32 v[22:23], v[22:23], v[26:27]
	v_lshlrev_b32_e32 v26, 16, v71
	v_and_b32_e32 v27, 0xffff0000, v71
	v_pk_add_f32 v[24:25], v[24:25], v[26:27]
	v_cvt_pk_bf16_f32 v22, v22, v23
	v_cvt_pk_bf16_f32 v23, v24, v25
	v_lshlrev_b32_e32 v24, 16, v72
	v_and_b32_e32 v25, 0xffff0000, v72
	v_pk_add_f32 v[14:15], v[14:15], v[24:25]
	ds_bpermute_b32 v200, v196, v38
	ds_bpermute_b32 v201, v196, v39
	ds_bpermute_b32 v202, v196, v40
	ds_bpermute_b32 v203, v196, v41
	s_waitcnt lgkmcnt(0)
	global_store_dwordx4 v[50:51], v[200:203], off offset:256
	v_cvt_pk_bf16_f32 v24, v14, v15
	v_lshlrev_b32_e32 v14, 16, v73
	v_and_b32_e32 v15, 0xffff0000, v73
	v_pk_add_f32 v[14:15], v[16:17], v[14:15]
	s_waitcnt vmcnt(5)
	v_lshlrev_b32_e32 v16, 16, v75
	v_cvt_pk_bf16_f32 v25, v14, v15
	v_lshl_add_u64 v[14:15], s[12:13], 0, v[94:95]
	v_lshl_add_u64 v[26:27], v[14:15], 0, v[168:169]
	v_lshlrev_b32_e32 v14, 16, v74
	v_and_b32_e32 v15, 0xffff0000, v74
	v_and_b32_e32 v17, 0xffff0000, v75
	v_pk_add_f32 v[14:15], v[18:19], v[14:15]
	v_pk_add_f32 v[16:17], v[20:21], v[16:17]
	v_cvt_pk_bf16_f32 v14, v14, v15
	v_cvt_pk_bf16_f32 v15, v16, v17
	v_lshlrev_b32_e32 v16, 16, v76
	v_and_b32_e32 v17, 0xffff0000, v76
	v_pk_add_f32 v[10:11], v[10:11], v[16:17]
	ds_bpermute_b32 v200, v196, v30
	ds_bpermute_b32 v201, v196, v31
	ds_bpermute_b32 v202, v196, v32
	ds_bpermute_b32 v203, v196, v33
	s_waitcnt lgkmcnt(0)
	global_store_dwordx4 v[42:43], v[200:203], off
	v_cvt_pk_bf16_f32 v16, v10, v11
	v_lshlrev_b32_e32 v10, 16, v77
	v_and_b32_e32 v11, 0xffff0000, v77
	v_pk_add_f32 v[10:11], v[12:13], v[10:11]
	ds_bpermute_b32 v200, v196, v22
	ds_bpermute_b32 v201, v196, v23
	ds_bpermute_b32 v202, v196, v24
	ds_bpermute_b32 v203, v196, v25
	s_waitcnt lgkmcnt(0)
	global_store_dwordx4 v[42:43], v[200:203], off offset:256
	v_cvt_pk_bf16_f32 v17, v10, v11
	s_waitcnt vmcnt(6)
	v_lshlrev_b32_e32 v10, 16, v66
	v_and_b32_e32 v11, 0xffff0000, v66
	v_pk_add_f32 v[6:7], v[6:7], v[10:11]
	v_lshlrev_b32_e32 v10, 16, v67
	v_and_b32_e32 v11, 0xffff0000, v67
	v_pk_add_f32 v[8:9], v[8:9], v[10:11]
	v_cvt_pk_bf16_f32 v6, v6, v7
	v_cvt_pk_bf16_f32 v7, v8, v9
	v_lshlrev_b32_e32 v8, 16, v68
	v_and_b32_e32 v9, 0xffff0000, v68
	v_pk_add_f32 v[2:3], v[2:3], v[8:9]
	ds_bpermute_b32 v200, v196, v14
	ds_bpermute_b32 v201, v196, v15
	ds_bpermute_b32 v202, v196, v16
	ds_bpermute_b32 v203, v196, v17
	s_waitcnt lgkmcnt(0)
	global_store_dwordx4 v[26:27], v[200:203], off
	v_cvt_pk_bf16_f32 v8, v2, v3
	v_lshlrev_b32_e32 v2, 16, v69
	v_and_b32_e32 v3, 0xffff0000, v69
	v_pk_add_f32 v[2:3], v[4:5], v[2:3]
	s_nop 0
	v_cvt_pk_bf16_f32 v9, v2, v3
	ds_bpermute_b32 v2, v185, v54
	ds_bpermute_b32 v200, v196, v6
	ds_bpermute_b32 v201, v196, v7
	ds_bpermute_b32 v202, v196, v8
	ds_bpermute_b32 v203, v196, v9
	s_waitcnt lgkmcnt(0)
	global_store_dwordx4 v[26:27], v[200:203], off offset:256
	s_waitcnt lgkmcnt(0)
	v_add_f32_e32 v2, v54, v2
	ds_bpermute_b32 v3, v186, v2
	s_and_saveexec_b64 s[30:31], vcc
	s_cbranch_execz .LBB0_465
	s_waitcnt lgkmcnt(0)
	v_add_f32_e32 v2, v2, v3
	global_store_dword v[98:99], v2, off offset:512
